# XCD-local grid barriers at seams 5, 7 and 8 (first pass): leader skips L2 write-back and cross-XCD hop; guarded by a run-time check that every blockIdx%8 group sits on one XCC; P7 rows XCD-local
# speedup vs baseline: 1.0095x; 1.0095x over previous
.LBB0_14:
	s_or_b64 exec, exec, s[4:5]
	s_barrier
	s_getreg_b32 s4, hwreg(HW_REG_XCC_ID, 0, 4)
	s_and_b32 s90, s4, 15
	v_cmp_eq_u32_e32 vcc, 0, v210
	s_and_saveexec_b64 s[4:5], vcc
	s_cbranch_execz .LBB0_17
	s_mov_b64 s[6:7], exec
	v_mbcnt_lo_u32_b32 v0, s6, 0
	v_mbcnt_hi_u32_b32 v0, s7, v0
	v_cmp_eq_u32_e32 vcc, 0, v0
	s_and_b64 s[8:9], exec, vcc
	s_mov_b64 exec, s[8:9]
	s_cbranch_execz .LBB0_17
	s_bcnt1_i32_b64 s6, s[6:7]
	s_lshl_b32 s8, s90, 8
	v_mov_b32_e32 v1, s6
	v_readlane_b32 s6, v254, 10
	v_mov_b32_e32 v0, s8
	v_readlane_b32 s7, v254, 11
	s_nop 4
	global_atomic_add v0, v1, s[6:7] offset:1024
	s_and_b32 s8, s101, 7
	s_lshl_b32 s8, s8, 4
	s_add_i32 s8, s8, s90
	s_lshl_b32 s8, s8, 2
	s_addk_i32 s8, 0x3700
	v_mov_b32_e32 v2, s8
	s_nop 0
	global_atomic_add v2, v1, s[6:7]

.LBB0_137:
	v_and_b32_e32 v0, 63, v210
	v_lshlrev_b32_e32 v0, 2, v0
	v_add_u32_e32 v0, 0x3700, v0
	v_readlane_b32 s0, v254, 10
	v_readlane_b32 s1, v254, 11
	s_nop 4
	global_load_dword v1, v0, s[0:1] sc1
	global_load_dword v2, v0, s[0:1] offset:256 sc1
	s_waitcnt vmcnt(0)
	v_cmp_ne_u32_e32 vcc, 0, v1
	s_nop 1
	s_bcnt1_i32_b64 s0, vcc
	v_cmp_ne_u32_e32 vcc, 0, v2
	s_nop 1
	s_bcnt1_i32_b64 s1, vcc
	s_add_i32 s0, s0, s1
	s_sub_i32 s0, s0, 8
	s_nop 3
	v_writelane_b32 v255, s0, 0
	s_cmp_lt_i32 s82, 2
	s_cselect_b64 s[0:1], -1, 0
	s_add_u32 s24, s78, 0x17e00000
	s_addc_u32 s25, s79, 0
	s_and_b64 s[4:5], s[0:1], s[4:5]
	s_cmp_lt_i32 s80, 0xa000
	s_cselect_b64 s[0:1], -1, 0
	v_writelane_b32 v254, s0, 50
	v_lshlrev_b32_e32 v216, 2, v217
	v_lshlrev_b32_e32 v212, 4, v217
	v_writelane_b32 v254, s1, 51
	s_and_b64 s[0:1], s[4:5], s[0:1]
	s_andn2_b64 vcc, exec, s[0:1]
	v_lshlrev_b32_e32 v214, 3, v217
	v_mbcnt_lo_u32_b32 v211, -1, 0
	s_cbranch_vccnz .LBB0_146
	s_lshl_b32 s8, s33, 4
	s_add_i32 s14, s80, s34
	s_ashr_i32 s81, s80, 31
	s_ashr_i32 s9, s8, 31
	s_ashr_i32 s15, s14, 31
	v_mov_b32_e32 v33, 0
	v_readlane_b32 s36, v254, 12
	v_or_b32_e32 v4, 0x300, v216
	s_lshl_b64 s[10:11], s[80:81], 11
	s_lshl_b64 s[12:13], s[8:9], 11
	s_lshl_b64 s[0:1], s[14:15], 12
	v_mbcnt_hi_u32_b32 v47, -1, v211
	v_mov_b32_e32 v213, v33
	v_readlane_b32 s40, v254, 16
	v_readlane_b32 s41, v254, 17
	v_or_b32_e32 v0, 0x100, v216
	v_or_b32_e32 v2, 0x200, v216
	v_mov_b32_e32 v215, v33
	v_lshlrev_b32_e32 v32, 1, v4
	s_add_u32 s20, s16, s0
	v_and_b32_e32 v1, 64, v47
	s_mov_b32 s7, 0
	v_lshl_add_u64 v[34:35], s[40:41], 0, v[212:213]
	v_lshl_add_u64 v[36:37], s[24:25], 0, v[214:215]
	v_lshl_add_u64 v[38:39], s[24:25], 0, v[32:33]
	v_lshl_add_u64 v[40:41], s[78:79], 0, v[214:215]
	s_addc_u32 s21, s17, s1
	s_lshl_b64 s[22:23], s[8:9], 12
	v_mov_b32_e32 v44, 0x358637bd
	s_mov_b32 s3, 0xf800000
	v_mov_b32_e32 v45, 0x260
	s_mov_b32 s35, 0x17e00000
	v_lshlrev_b32_e32 v32, 2, v4
	v_lshlrev_b32_e32 v46, 2, v216
	v_add_u32_e32 v48, 64, v1
	v_xor_b32_e32 v49, 1, v47
	v_xor_b32_e32 v50, 2, v47
	v_xor_b32_e32 v51, 4, v47
	v_xor_b32_e32 v52, 8, v47
	v_xor_b32_e32 v53, 16, v47
	v_xor_b32_e32 v54, 32, v47
	v_lshlrev_b32_e32 v55, 2, v0
	v_lshlrev_b32_e32 v56, 2, v2
	s_mov_b64 s[26:27], s[80:81]
	v_readlane_b32 s37, v254, 13
	v_readlane_b32 s38, v254, 14
	v_readlane_b32 s39, v254, 15
	v_readlane_b32 s42, v254, 18
	v_readlane_b32 s43, v254, 19
	v_readlane_b32 s44, v254, 20
	v_readlane_b32 s45, v254, 21
	v_readlane_b32 s46, v254, 22
	v_readlane_b32 s47, v254, 23
	v_readlane_b32 s48, v254, 24
	v_readlane_b32 s49, v254, 25
	v_readlane_b32 s50, v254, 26
	v_readlane_b32 s51, v254, 27
	s_branch .LBB0_141

.LBB0_742:
	s_andn2_saveexec_b64 s[8:9], s[8:9]
	s_cbranch_execz .LBB0_760
	v_readlane_b32 s3, v255, 0
	s_cmp_lg_u32 s3, 0
	s_cbranch_scc0 .Lloc_s5
.Lglob_s5:
	s_mov_b64 s[8:9], exec
	buffer_wbl2 sc1
	s_waitcnt lgkmcnt(0)
	s_waitcnt vmcnt(0)
	v_mbcnt_lo_u32_b32 v1, s8, 0
	v_mbcnt_hi_u32_b32 v1, s9, v1
	v_cmp_eq_u32_e32 vcc, 0, v1
	s_and_saveexec_b64 s[10:11], vcc
	s_cbranch_execz .LBB0_745
	s_bcnt1_i32_b64 s3, s[8:9]
	v_mov_b32_e32 v2, 0x1e03000
	v_mov_b32_e32 v3, s3
	global_atomic_add v2, v2, v3, s[78:79] offset:1024 sc0

.Lloc_s5:
	v_mov_b32_e32 v0, 0x2000
	v_mov_b32_e32 v1, 1
	s_waitcnt vmcnt(0)
	buffer_inv sc1
	global_atomic_add v0, v1, s[6:7] offset:1024
	s_waitcnt vmcnt(0)

.LBB0_828:
	s_cmp_lt_i32 s82, 8
	s_cselect_b64 s[4:5], -1, 0
	s_and_b64 s[4:5], s[4:5], s[0:1]
	s_and_b64 s[0:1], s[4:5], s[84:85]
	s_andn2_b64 vcc, exec, s[0:1]
	s_cbranch_vccnz .LBB0_835
	v_mov_b32_e32 v5, 0
	v_readlane_b32 s8, v254, 0
	s_ashr_i32 s81, s80, 31
	s_lshr_b32 s40, s80, 8
	s_mulk_i32 s40, 0x1400
	s_and_b32 s41, s80, 0xff
	s_add_i32 s43, s40, s41
	s_add_i32 s40, s43, 0x1200
	s_mov_b32 s41, 0
	v_mov_b32_e32 v213, v5
	v_readlane_b32 s9, v254, 1
	s_movk_i32 s6, 0xfe00
	s_lshl_b64 s[0:1], s[40:41], 11
	v_lshl_add_u64 v[6:7], s[8:9], 0, v[212:213]
	s_add_u32 s8, s78, s0
	s_addc_u32 s9, s79, s1
	s_add_i32 s16, s40, 0x100
	v_readlane_b32 s10, v254, 2
	v_readlane_b32 s11, v254, 3
	v_readlane_b32 s12, v254, 4
	v_readlane_b32 s13, v254, 5
	v_readlane_b32 s14, v254, 6
	v_readlane_b32 s15, v254, 7
	s_ashr_i32 s7, s6, 31
	s_ashr_i32 s17, s16, 31
	s_lshl_b64 s[10:11], s[6:7], 11
	s_lshl_b64 s[12:13], s[40:41], 10
	s_lshl_b64 s[14:15], s[6:7], 10
	s_lshl_b64 s[20:21], s[16:17], 11
	s_add_u32 s16, s76, s20
	s_addc_u32 s17, s77, s21
	s_add_u32 s18, s76, s0
	v_or_b32_e32 v8, 0x300, v216
	s_addc_u32 s19, s77, s1
	v_mbcnt_hi_u32_b32 v47, -1, v211
	v_or_b32_e32 v0, 0x100, v216
	v_or_b32_e32 v2, 0x200, v216
	v_lshlrev_b32_e32 v4, 1, v8
	s_add_u32 s20, s78, s20
	v_and_b32_e32 v1, 64, v47
	s_waitcnt lgkmcnt(0)
	v_lshl_add_u64 v[10:11], s[22:23], 0, v[4:5]
	v_mov_b32_e32 v215, v5
	s_addc_u32 s21, s79, s21
	v_mov_b32_e32 v9, 0x358637bd
	s_mov_b32 s3, 0xf800000
	v_mov_b32_e32 v46, 0x260
	s_brev_b32 s7, 64
	v_add_u32_e32 v48, 64, v1
	v_xor_b32_e32 v49, 1, v47
	v_xor_b32_e32 v50, 2, v47
	v_xor_b32_e32 v51, 4, v47
	v_xor_b32_e32 v52, 8, v47
	v_xor_b32_e32 v53, 16, v47
	v_xor_b32_e32 v54, 32, v47
	v_lshlrev_b32_e32 v55, 2, v216
	v_lshlrev_b32_e32 v56, 2, v0
	v_lshlrev_b32_e32 v57, 2, v2
	s_mov_b32 s35, s40
	s_branch .LBB0_831

.LBB0_831:
	s_add_i32 s0, s35, 0xffffe000
	s_add_i32 s36, s35, 0x100
	s_ashr_i32 s0, s0, 12
	s_cmpk_gt_i32 s35, 0x1fff
	s_cselect_b32 s24, s0, 8
	s_mov_b64 s[0:1], -1
	s_cmp_gt_i32 s36, 0x9fff
	s_mul_i32 s28, s24, 0x1800
	v_lshl_add_u64 v[14:15], s[18:19], 0, v[214:215]
	v_lshl_add_u64 v[12:13], s[8:9], 0, v[214:215]
	s_cbranch_scc0 .LBB0_833
	global_load_dwordx2 v[24:25], v[14:15], off
	global_load_dwordx2 v[26:27], v[14:15], off offset:512
	global_load_dwordx2 v[28:29], v[14:15], off offset:1024
	global_load_dwordx2 v[30:31], v[14:15], off offset:1536
	s_ashr_i32 s29, s28, 31
	s_lshl_b64 s[0:1], s[28:29], 2
	s_add_u32 s24, s78, s0
	s_addc_u32 s25, s79, s1
	s_add_u32 s26, s24, 0x3000
	s_addc_u32 s27, s25, 0
	s_add_u32 s30, s24, 0x4000
	global_load_dwordx4 v[0:3], v[6:7], off
	s_addc_u32 s31, s25, 0
	global_load_dwordx4 v[16:19], v55, s[30:31]
	global_load_dwordx4 v[20:23], v55, s[26:27]
	v_cmp_lt_i32_e32 vcc, v49, v48
	s_waitcnt vmcnt(0)
	v_lshlrev_b32_e32 v32, 16, v24
	v_cndmask_b32_e32 v4, v47, v49, vcc
	v_and_b32_e32 v33, 0xffff0000, v24
	v_lshlrev_b32_e32 v24, 16, v25
	v_and_b32_e32 v25, 0xffff0000, v25
	v_lshlrev_b32_e32 v66, 2, v4
	v_lshlrev_b32_e32 v35, 16, v27
	v_lshlrev_b32_e32 v34, 16, v26
	v_and_b32_e32 v27, 0xffff0000, v27
	v_and_b32_e32 v26, 0xffff0000, v26
	v_lshlrev_b32_e32 v36, 16, v28
	v_and_b32_e32 v37, 0xffff0000, v28
	v_lshlrev_b32_e32 v28, 16, v29
	v_and_b32_e32 v29, 0xffff0000, v29
	v_lshlrev_b32_e32 v39, 16, v30
	v_mul_f32_e32 v4, v25, v25
	v_mul_f32_e32 v38, v33, v33
	v_pk_mul_f32 v[42:43], v[26:27], v[26:27]
	v_mov_b32_e32 v45, v39
	v_mul_f32_e32 v44, v29, v29
	v_pk_fma_f32 v[58:59], v[24:25], v[24:25], v[4:5] op_sel_hi:[1,1,0]
	v_pk_fma_f32 v[60:61], v[32:33], v[32:33], v[38:39] op_sel_hi:[1,1,0]
	v_and_b32_e32 v41, 0xffff0000, v30
	v_lshlrev_b32_e32 v30, 16, v31
	v_and_b32_e32 v31, 0xffff0000, v31
	v_mul_f32_e32 v40, v37, v37
	v_pk_fma_f32 v[42:43], v[34:35], v[34:35], v[42:43]
	v_pk_fma_f32 v[64:65], v[28:29], v[28:29], v[44:45] op_sel_hi:[1,1,0]
	v_mov_b32_e32 v38, v60
	v_mov_b32_e32 v44, v58
	v_mul_f32_e32 v67, v41, v41
	v_mul_f32_e32 v68, v30, v30
	v_mul_f32_e32 v69, v31, v31
	v_pk_fma_f32 v[62:63], v[36:37], v[36:37], v[40:41] op_sel_hi:[1,1,0]
	v_pk_add_f32 v[58:59], v[60:61], v[58:59]
	v_pk_add_f32 v[42:43], v[42:43], v[42:43] op_sel:[0,1] op_sel_hi:[1,0]
	v_pk_mul_f32 v[44:45], v[38:39], v[44:45]
	v_mov_b32_e32 v63, v68
	v_mov_b32_e32 v65, v69
	v_mov_b32_e32 v43, v67
	v_mov_b32_e32 v59, v45
	v_pk_add_f32 v[60:61], v[62:63], v[64:65]
	v_pk_add_f32 v[42:43], v[58:59], v[42:43]
	v_cmp_lt_i32_e32 vcc, v50, v48
	v_pk_add_f32 v[42:43], v[42:43], v[60:61]
	v_pk_add_f32 v[18:19], v[18:19], 1.0 op_sel_hi:[1,0]
	v_add_f32_e32 v4, v42, v43
	ds_bpermute_b32 v38, v66, v4
	v_cndmask_b32_e32 v40, v47, v50, vcc
	v_lshlrev_b32_e32 v40, 2, v40
	v_cmp_lt_i32_e32 vcc, v51, v48
	v_add_co_u32_e64 v42, s[0:1], s7, v12
	s_waitcnt lgkmcnt(0)
	v_add_f32_e32 v4, v4, v38
	ds_bpermute_b32 v38, v40, v4
	v_cndmask_b32_e32 v40, v47, v51, vcc
	v_lshlrev_b32_e32 v40, 2, v40
	v_cmp_lt_i32_e32 vcc, v52, v48
	v_addc_co_u32_e64 v43, s[0:1], 0, v13, s[0:1]
	s_waitcnt lgkmcnt(0)
	v_add_f32_e32 v4, v4, v38
	ds_bpermute_b32 v38, v40, v4
	v_cndmask_b32_e32 v40, v47, v52, vcc
	v_lshlrev_b32_e32 v40, 2, v40
	v_cmp_lt_i32_e32 vcc, v53, v48
	v_pk_add_f32 v[16:17], v[16:17], 1.0 op_sel_hi:[1,0]
	s_waitcnt lgkmcnt(0)
	v_add_f32_e32 v4, v4, v38
	ds_bpermute_b32 v38, v40, v4
	v_cndmask_b32_e32 v40, v47, v53, vcc
	v_lshlrev_b32_e32 v40, 2, v40
	v_cmp_lt_i32_e32 vcc, v54, v48
	s_waitcnt lgkmcnt(0)
	v_add_f32_e32 v4, v4, v38
	ds_bpermute_b32 v38, v40, v4
	v_cndmask_b32_e32 v40, v47, v54, vcc
	v_lshlrev_b32_e32 v40, 2, v40
	s_waitcnt lgkmcnt(0)
	v_add_f32_e32 v4, v4, v38
	ds_bpermute_b32 v38, v40, v4
	s_waitcnt lgkmcnt(0)
	v_add_f32_e32 v4, v4, v38
	v_fmamk_f32 v4, v4, 0x3a800000, v9
	v_mul_f32_e32 v38, 0x4f800000, v4
	v_cmp_gt_f32_e32 vcc, s3, v4
	s_nop 1
	v_cndmask_b32_e32 v4, v4, v38, vcc
	v_sqrt_f32_e32 v38, v4
	s_nop 0
	v_add_u32_e32 v40, -1, v38
	v_add_u32_e32 v44, 1, v38
	v_fma_f32 v45, -v40, v38, v4
	v_fma_f32 v58, -v44, v38, v4
	v_cmp_ge_f32_e64 s[0:1], 0, v45
	s_nop 1
	v_cndmask_b32_e64 v38, v38, v40, s[0:1]
	v_cmp_lt_f32_e64 s[0:1], 0, v58
	s_nop 1
	v_cndmask_b32_e64 v38, v38, v44, s[0:1]
	v_mul_f32_e32 v40, 0x37800000, v38
	v_cndmask_b32_e32 v38, v38, v40, vcc
	v_cmp_class_f32_e32 vcc, v4, v46
	s_nop 1
	v_cndmask_b32_e32 v4, v38, v4, vcc
	v_div_scale_f32 v38, s[0:1], v4, v4, 1.0
	v_rcp_f32_e32 v40, v38
	v_div_scale_f32 v44, vcc, 1.0, v4, 1.0
	s_mov_b64 s[0:1], 0
	v_fma_f32 v45, -v38, v40, 1.0
	v_fmac_f32_e32 v40, v45, v40
	v_mul_f32_e32 v45, v44, v40
	v_fma_f32 v58, -v38, v45, v44
	v_fmac_f32_e32 v45, v58, v40
	v_fma_f32 v38, -v38, v45, v44
	v_div_fmas_f32 v38, v38, v40, v45
	v_div_fixup_f32 v4, v38, v4, 1.0
	v_pk_mul_f32 v[24:25], v[4:5], v[24:25] op_sel_hi:[0,1]
	v_pk_mul_f32 v[32:33], v[4:5], v[32:33] op_sel_hi:[0,1]
	v_pk_mul_f32 v[0:1], v[0:1], v[32:33]
	v_pk_mul_f32 v[2:3], v[2:3], v[24:25]
	v_pk_fma_f32 v[0:1], v[16:17], v[0:1], v[20:21]
	v_pk_fma_f32 v[2:3], v[18:19], v[2:3], v[22:23]
	v_cvt_pk_bf16_f32 v0, v0, v1
	v_cvt_pk_bf16_f32 v1, v2, v3
	global_store_dwordx2 v[42:43], v[0:1], off
	global_load_dwordx4 v[0:3], v[6:7], off offset:1024
	s_nop 0
	global_load_dwordx4 v[16:19], v56, s[30:31]
	global_load_dwordx4 v[20:23], v56, s[26:27]
	v_mov_b32_e32 v24, v35
	v_mov_b32_e32 v25, v27
	v_mov_b32_e32 v35, v26
	v_pk_mul_f32 v[24:25], v[4:5], v[24:25] op_sel_hi:[0,1]
	v_pk_mul_f32 v[26:27], v[4:5], v[34:35] op_sel_hi:[0,1]
	v_mov_b32_e32 v40, v39
	s_waitcnt vmcnt(2)
	v_pk_mul_f32 v[0:1], v[0:1], v[26:27]
	v_pk_mul_f32 v[2:3], v[2:3], v[24:25]
	s_waitcnt vmcnt(1)
	v_pk_add_f32 v[18:19], v[18:19], 1.0 op_sel_hi:[1,0]
	v_pk_add_f32 v[16:17], v[16:17], 1.0 op_sel_hi:[1,0]
	s_waitcnt vmcnt(0)
	v_pk_fma_f32 v[2:3], v[18:19], v[2:3], v[22:23]
	v_pk_fma_f32 v[0:1], v[16:17], v[0:1], v[20:21]
	v_pk_mul_f32 v[24:25], v[4:5], v[28:29] op_sel_hi:[0,1]
	v_cvt_pk_bf16_f32 v0, v0, v1
	v_cvt_pk_bf16_f32 v1, v2, v3
	global_store_dwordx2 v[42:43], v[0:1], off offset:512
	global_load_dwordx4 v[0:3], v[6:7], off offset:2048
	s_nop 0
	global_load_dwordx4 v[16:19], v57, s[30:31]
	global_load_dwordx4 v[20:23], v57, s[26:27]
	v_pk_mul_f32 v[26:27], v[4:5], v[36:37] op_sel_hi:[0,1]
	s_waitcnt vmcnt(2)
	v_pk_mul_f32 v[0:1], v[0:1], v[26:27]
	v_pk_mul_f32 v[2:3], v[2:3], v[24:25]
	s_waitcnt vmcnt(1)
	v_pk_add_f32 v[18:19], v[18:19], 1.0 op_sel_hi:[1,0]
	v_pk_add_f32 v[16:17], v[16:17], 1.0 op_sel_hi:[1,0]
	s_waitcnt vmcnt(0)
	v_pk_fma_f32 v[2:3], v[18:19], v[2:3], v[22:23]
	v_pk_fma_f32 v[0:1], v[16:17], v[0:1], v[20:21]
	v_pk_mul_f32 v[16:17], v[30:31], v[4:5] op_sel_hi:[1,0]
	v_cvt_pk_bf16_f32 v0, v0, v1
	v_cvt_pk_bf16_f32 v1, v2, v3
	global_store_dwordx2 v[42:43], v[0:1], off offset:1024
	global_load_dwordx4 v[0:3], v[6:7], off offset:3072
	v_pk_mul_f32 v[18:19], v[40:41], v[4:5] op_sel_hi:[1,0]
	s_waitcnt vmcnt(0)
	v_pk_mul_f32 v[2:3], v[16:17], v[2:3]
	v_pk_mul_f32 v[0:1], v[18:19], v[0:1]

.LBB0_933:
	s_andn2_saveexec_b64 s[10:11], s[10:11]
	s_cbranch_execz .LBB0_951
	v_readlane_b32 s3, v255, 0
	s_cmp_eq_u32 s100, 9
	s_cbranch_scc1 .Lglob_s8
	s_cmp_lg_u32 s3, 0
	s_cbranch_scc0 .Lloc_s8
.Lglob_s8:
	s_mov_b64 s[10:11], exec
	buffer_wbl2 sc1
	s_waitcnt lgkmcnt(0)
	s_waitcnt vmcnt(0)
	v_mbcnt_lo_u32_b32 v1, s10, 0
	v_mbcnt_hi_u32_b32 v1, s11, v1
	v_cmp_eq_u32_e32 vcc, 0, v1
	s_and_saveexec_b64 s[12:13], vcc
	s_cbranch_execz .LBB0_936
	s_bcnt1_i32_b64 s3, s[10:11]
	v_mov_b32_e32 v2, 0x1e03000
	v_mov_b32_e32 v3, s3
	global_atomic_add v2, v2, v3, s[78:79] offset:1024 sc0

.Lloc_s8:
	v_mov_b32_e32 v0, 0x2000
	v_mov_b32_e32 v1, 1
	s_waitcnt vmcnt(0)
	buffer_inv sc1
	global_atomic_add v0, v1, s[8:9] offset:1024
	s_waitcnt vmcnt(0)

	.amdhsa_kernel _ZN2pb8mega_fwdENS_4ArgsE
		.amdhsa_group_segment_fixed_size 0
		.amdhsa_private_segment_fixed_size 0
		.amdhsa_kernarg_size 512
		.amdhsa_user_sgpr_count 2
		.amdhsa_user_sgpr_dispatch_ptr 0
		.amdhsa_user_sgpr_queue_ptr 0
		.amdhsa_user_sgpr_kernarg_segment_ptr 1
		.amdhsa_user_sgpr_dispatch_id 0
		.amdhsa_user_sgpr_kernarg_preload_length 0
		.amdhsa_user_sgpr_kernarg_preload_offset 0
		.amdhsa_user_sgpr_private_segment_size 0
		.amdhsa_uses_dynamic_stack 0
		.amdhsa_enable_private_segment 0
		.amdhsa_system_sgpr_workgroup_id_x 1
		.amdhsa_system_sgpr_workgroup_id_y 0
		.amdhsa_system_sgpr_workgroup_id_z 0
		.amdhsa_system_sgpr_workgroup_info 0
		.amdhsa_system_vgpr_workitem_id 2
		.amdhsa_next_free_vgpr 256
		.amdhsa_next_free_sgpr 102
		.amdhsa_accum_offset 256
		.amdhsa_reserve_vcc 1
		.amdhsa_float_round_mode_32 0
		.amdhsa_float_round_mode_16_64 0
		.amdhsa_float_denorm_mode_32 3
		.amdhsa_float_denorm_mode_16_64 3
		.amdhsa_dx10_clamp 1
		.amdhsa_ieee_mode 1
		.amdhsa_fp16_overflow 0
		.amdhsa_tg_split 0
		.amdhsa_exception_fp_ieee_invalid_op 0
		.amdhsa_exception_fp_denorm_src 0
		.amdhsa_exception_fp_ieee_div_zero 0
		.amdhsa_exception_fp_ieee_overflow 0
		.amdhsa_exception_fp_ieee_underflow 0
		.amdhsa_exception_fp_ieee_inexact 0
		.amdhsa_exception_int_div_zero 0
	.end_amdhsa_kernel

amdhsa.kernels:
  - .agpr_count:     0
    .args:
      - .offset:         0
        .size:           256
        .value_kind:     by_value
      - .offset:         256
        .size:           4
        .value_kind:     hidden_block_count_x
      - .offset:         260
        .size:           4
        .value_kind:     hidden_block_count_y
      - .offset:         264
        .size:           4
        .value_kind:     hidden_block_count_z
      - .offset:         268
        .size:           2
        .value_kind:     hidden_group_size_x
      - .offset:         270
        .size:           2
        .value_kind:     hidden_group_size_y
      - .offset:         272
        .size:           2
        .value_kind:     hidden_group_size_z
      - .offset:         274
        .size:           2
        .value_kind:     hidden_remainder_x
      - .offset:         276
        .size:           2
        .value_kind:     hidden_remainder_y
      - .offset:         278
        .size:           2
        .value_kind:     hidden_remainder_z
      - .offset:         296
        .size:           8
        .value_kind:     hidden_global_offset_x
      - .offset:         304
        .size:           8
        .value_kind:     hidden_global_offset_y
      - .offset:         312
        .size:           8
        .value_kind:     hidden_global_offset_z
      - .offset:         320
        .size:           2
        .value_kind:     hidden_grid_dims
      - .offset:         344
        .size:           8
        .value_kind:     hidden_multigrid_sync_arg
      - .offset:         376
        .size:           4
        .value_kind:     hidden_dynamic_lds_size
    .group_segment_fixed_size: 0
    .kernarg_segment_align: 8
    .kernarg_segment_size: 512
    .language:       OpenCL C
    .language_version:
      - 2
      - 0
    .max_flat_workgroup_size: 512
    .name:           _ZN2pb8mega_fwdENS_4ArgsE
    .private_segment_fixed_size: 0
    .sgpr_count:     108
    .sgpr_spill_count: 74
    .symbol:         _ZN2pb8mega_fwdENS_4ArgsE.kd
    .uniform_work_group_size: 1
    .uses_dynamic_stack: false
    .vgpr_count:     256
    .vgpr_spill_count: 0
    .wavefront_size: 64
